# combine: split-KV partial loop replaced by straight-line code with all part loads issued first
# speedup vs baseline: 1.0246x; 1.0021x over previous
; DI void unpack8(u32x4 v, float* x) { x[0] = bflo(v.x); x[1] = bfhi(v.x); x[2] = bflo(v.y); x[3] = bfhi(v.y); x[4] = bflo(v.z); x[5] = bfhi(v.z); x[6] = bflo(v.w); x[7] = bfhi(v.w); }
; DI void combine_task(const Params& p, int layer, int tile) {
;     ...
;       for (int pi = 0; pi < nparts; ++pi) {
;         const int pcol = pi == 0 ? A_V : (pi == 1 ? A_Z : (pi == 2 ? B_V : D_X));
;         float a[16];
;         unpack8(*(const u32x4*)(row + pcol + col), a); unpack8(*(const u32x4*)(row + pcol + col + 8), a + 8);
; #pragma unroll
;         for (int e = 0; e < 16; ++e) o[e] += a[e];
;         l += lbuf[((size_t)pi * T_TOK + t) * 4 + h];
;       }
.LBB0_22:
.LBB0_23:
	s_mov_b64 s[34:35], 0x100
	v_lshl_add_u64 v[26:27], s[34:35], 1, v[40:41]
	global_load_dword v21, v[18:19], off
	global_load_dwordx4 v[22:25], v[26:27], off
	global_load_dwordx4 v[26:29], v[26:27], off offset:16
	v_lshl_add_u64 v[18:19], v[18:19], 0, s[96:97]
	s_and_b64 vcc, exec, s[0:1]
	s_cbranch_vccnz .Lcmb0_one
	s_mov_b64 s[34:35], 0x200
	v_lshl_add_u64 v[78:79], s[34:35], 1, v[40:41]
	global_load_dword v76, v[18:19], off
	global_load_dwordx4 v[80:83], v[78:79], off
	global_load_dwordx4 v[84:87], v[78:79], off offset:16
	v_lshl_add_u64 v[18:19], v[18:19], 0, s[96:97]
	s_mov_b32 s34, s45
	s_mov_b32 s35, 0
	v_lshl_add_u64 v[90:91], s[34:35], 1, v[40:41]
	global_load_dword v88, v[18:19], off
	global_load_dwordx4 v[92:95], v[90:91], off
	global_load_dwordx4 v[96:99], v[90:91], off offset:16
	v_lshl_add_u64 v[18:19], v[18:19], 0, s[96:97]
	s_mov_b64 s[34:35], 0xa00
	v_lshl_add_u64 v[102:103], s[34:35], 1, v[40:41]
	global_load_dword v100, v[18:19], off
	global_load_dwordx4 v[104:107], v[102:103], off
	global_load_dwordx4 v[108:111], v[102:103], off offset:16
	v_lshl_add_u64 v[18:19], v[18:19], 0, s[96:97]
	s_waitcnt vmcnt(11)
	v_add_f32_e32 v20, v20, v21
	s_waitcnt vmcnt(10)
	v_lshlrev_b32_e32 v30, 16, v22
	v_and_b32_e32 v31, 0xffff0000, v22
	v_lshlrev_b32_e32 v22, 16, v23
	v_and_b32_e32 v23, 0xffff0000, v23
	v_lshlrev_b32_e32 v32, 16, v24
	v_and_b32_e32 v33, 0xffff0000, v24
	v_lshlrev_b32_e32 v24, 16, v25
	v_and_b32_e32 v25, 0xffff0000, v25
	s_waitcnt vmcnt(9)
	v_lshlrev_b32_e32 v34, 16, v26
	v_and_b32_e32 v35, 0xffff0000, v26
	v_lshlrev_b32_e32 v26, 16, v27
	v_and_b32_e32 v27, 0xffff0000, v27
	v_lshlrev_b32_e32 v36, 16, v28
	v_and_b32_e32 v37, 0xffff0000, v28
	v_lshlrev_b32_e32 v28, 16, v29
	v_and_b32_e32 v29, 0xffff0000, v29
	v_pk_add_f32 v[16:17], v[16:17], v[30:31]
	v_pk_add_f32 v[14:15], v[14:15], v[22:23]
	v_pk_add_f32 v[12:13], v[12:13], v[32:33]
	v_pk_add_f32 v[6:7], v[6:7], v[24:25]
	v_pk_add_f32 v[10:11], v[10:11], v[34:35]
	v_pk_add_f32 v[4:5], v[4:5], v[26:27]
	v_pk_add_f32 v[2:3], v[2:3], v[36:37]
	v_pk_add_f32 v[0:1], v[0:1], v[28:29]
	s_waitcnt vmcnt(8)
	v_add_f32_e32 v20, v20, v76
	s_waitcnt vmcnt(7)
	v_lshlrev_b32_e32 v30, 16, v80
	v_and_b32_e32 v31, 0xffff0000, v80
	v_lshlrev_b32_e32 v80, 16, v81
	v_and_b32_e32 v81, 0xffff0000, v81
	v_lshlrev_b32_e32 v32, 16, v82
	v_and_b32_e32 v33, 0xffff0000, v82
	v_lshlrev_b32_e32 v82, 16, v83
	v_and_b32_e32 v83, 0xffff0000, v83
	s_waitcnt vmcnt(6)
	v_lshlrev_b32_e32 v34, 16, v84
	v_and_b32_e32 v35, 0xffff0000, v84
	v_lshlrev_b32_e32 v84, 16, v85
	v_and_b32_e32 v85, 0xffff0000, v85
	v_lshlrev_b32_e32 v36, 16, v86
	v_and_b32_e32 v37, 0xffff0000, v86
	v_lshlrev_b32_e32 v86, 16, v87
	v_and_b32_e32 v87, 0xffff0000, v87
	v_pk_add_f32 v[16:17], v[16:17], v[30:31]
	v_pk_add_f32 v[14:15], v[14:15], v[80:81]
	v_pk_add_f32 v[12:13], v[12:13], v[32:33]
	v_pk_add_f32 v[6:7], v[6:7], v[82:83]
	v_pk_add_f32 v[10:11], v[10:11], v[34:35]
	v_pk_add_f32 v[4:5], v[4:5], v[84:85]
	v_pk_add_f32 v[2:3], v[2:3], v[36:37]
	v_pk_add_f32 v[0:1], v[0:1], v[86:87]
	s_waitcnt vmcnt(5)
	v_add_f32_e32 v20, v20, v88
	s_waitcnt vmcnt(4)
	v_lshlrev_b32_e32 v30, 16, v92
	v_and_b32_e32 v31, 0xffff0000, v92
	v_lshlrev_b32_e32 v92, 16, v93
	v_and_b32_e32 v93, 0xffff0000, v93
	v_lshlrev_b32_e32 v32, 16, v94
	v_and_b32_e32 v33, 0xffff0000, v94
	v_lshlrev_b32_e32 v94, 16, v95
	v_and_b32_e32 v95, 0xffff0000, v95
	s_waitcnt vmcnt(3)
	v_lshlrev_b32_e32 v34, 16, v96
	v_and_b32_e32 v35, 0xffff0000, v96
	v_lshlrev_b32_e32 v96, 16, v97
	v_and_b32_e32 v97, 0xffff0000, v97
	v_lshlrev_b32_e32 v36, 16, v98
	v_and_b32_e32 v37, 0xffff0000, v98
	v_lshlrev_b32_e32 v98, 16, v99
	v_and_b32_e32 v99, 0xffff0000, v99
	v_pk_add_f32 v[16:17], v[16:17], v[30:31]
	v_pk_add_f32 v[14:15], v[14:15], v[92:93]
	v_pk_add_f32 v[12:13], v[12:13], v[32:33]
	v_pk_add_f32 v[6:7], v[6:7], v[94:95]
	v_pk_add_f32 v[10:11], v[10:11], v[34:35]
	v_pk_add_f32 v[4:5], v[4:5], v[96:97]
	v_pk_add_f32 v[2:3], v[2:3], v[36:37]
	v_pk_add_f32 v[0:1], v[0:1], v[98:99]
	s_waitcnt vmcnt(2)
	v_add_f32_e32 v20, v20, v100
	s_waitcnt vmcnt(1)
	v_lshlrev_b32_e32 v30, 16, v104
	v_and_b32_e32 v31, 0xffff0000, v104
	v_lshlrev_b32_e32 v104, 16, v105
	v_and_b32_e32 v105, 0xffff0000, v105
	v_lshlrev_b32_e32 v32, 16, v106
	v_and_b32_e32 v33, 0xffff0000, v106
	v_lshlrev_b32_e32 v106, 16, v107
	v_and_b32_e32 v107, 0xffff0000, v107
	s_waitcnt vmcnt(0)
	v_lshlrev_b32_e32 v34, 16, v108
	v_and_b32_e32 v35, 0xffff0000, v108
	v_lshlrev_b32_e32 v108, 16, v109
	v_and_b32_e32 v109, 0xffff0000, v109
	v_lshlrev_b32_e32 v36, 16, v110
	v_and_b32_e32 v37, 0xffff0000, v110
	v_lshlrev_b32_e32 v110, 16, v111
	v_and_b32_e32 v111, 0xffff0000, v111
	v_pk_add_f32 v[16:17], v[16:17], v[30:31]
	v_pk_add_f32 v[14:15], v[14:15], v[104:105]
	v_pk_add_f32 v[12:13], v[12:13], v[32:33]
	v_pk_add_f32 v[6:7], v[6:7], v[106:107]
	v_pk_add_f32 v[10:11], v[10:11], v[34:35]
	v_pk_add_f32 v[4:5], v[4:5], v[108:109]
	v_pk_add_f32 v[2:3], v[2:3], v[36:37]
	v_pk_add_f32 v[0:1], v[0:1], v[110:111]
	s_mov_b32 s6, 4
	s_branch .Lcmb0_done
.Lcmb0_one:
	s_waitcnt vmcnt(2)
	v_add_f32_e32 v20, v20, v21
	s_waitcnt vmcnt(1)
	v_lshlrev_b32_e32 v30, 16, v22
	v_and_b32_e32 v31, 0xffff0000, v22
	v_lshlrev_b32_e32 v22, 16, v23
	v_and_b32_e32 v23, 0xffff0000, v23
	v_lshlrev_b32_e32 v32, 16, v24
	v_and_b32_e32 v33, 0xffff0000, v24
	v_lshlrev_b32_e32 v24, 16, v25
	v_and_b32_e32 v25, 0xffff0000, v25
	s_waitcnt vmcnt(0)
	v_lshlrev_b32_e32 v34, 16, v26
	v_and_b32_e32 v35, 0xffff0000, v26
	v_lshlrev_b32_e32 v26, 16, v27
	v_and_b32_e32 v27, 0xffff0000, v27
	v_lshlrev_b32_e32 v36, 16, v28
	v_and_b32_e32 v37, 0xffff0000, v28
	v_lshlrev_b32_e32 v28, 16, v29
	v_and_b32_e32 v29, 0xffff0000, v29
	v_pk_add_f32 v[16:17], v[16:17], v[30:31]
	v_pk_add_f32 v[14:15], v[14:15], v[22:23]
	v_pk_add_f32 v[12:13], v[12:13], v[32:33]
	v_pk_add_f32 v[6:7], v[6:7], v[24:25]
	v_pk_add_f32 v[10:11], v[10:11], v[34:35]
	v_pk_add_f32 v[4:5], v[4:5], v[26:27]
	v_pk_add_f32 v[2:3], v[2:3], v[36:37]
	v_pk_add_f32 v[0:1], v[0:1], v[28:29]
	s_mov_b32 s6, 1
.Lcmb0_done:
	s_branch .LBB0_28

; DI void unpack8(u32x4 v, float* x) { x[0] = bflo(v.x); x[1] = bfhi(v.x); x[2] = bflo(v.y); x[3] = bfhi(v.y); x[4] = bflo(v.z); x[5] = bfhi(v.z); x[6] = bflo(v.w); x[7] = bfhi(v.w); }
; DI void combine_task(const Params& p, int layer, int tile) {
;     ...
;       for (int pi = 0; pi < nparts; ++pi) {
;         const int pcol = pi == 0 ? A_V : (pi == 1 ? A_Z : (pi == 2 ? B_V : D_X));
;         float a[16];
;         unpack8(*(const u32x4*)(row + pcol + col), a); unpack8(*(const u32x4*)(row + pcol + col + 8), a + 8);
; #pragma unroll
;         for (int e = 0; e < 16; ++e) o[e] += a[e];
;         l += lbuf[((size_t)pi * T_TOK + t) * 4 + h];
;       }
.LBB0_29:
.LBB0_30:
	s_mov_b64 s[34:35], 0x100
	v_lshl_add_u64 v[24:25], s[34:35], 1, v[40:41]
	global_load_dword v19, v[16:17], off
	global_load_dwordx4 v[20:23], v[24:25], off offset:128
	global_load_dwordx4 v[24:27], v[24:25], off offset:144
	v_lshl_add_u64 v[16:17], v[16:17], 0, s[96:97]
	s_and_b64 vcc, exec, s[0:1]
	s_cbranch_vccnz .Lcmb1_one
	s_mov_b64 s[34:35], 0x200
	v_lshl_add_u64 v[78:79], s[34:35], 1, v[40:41]
	global_load_dword v76, v[16:17], off
	global_load_dwordx4 v[80:83], v[78:79], off offset:128
	global_load_dwordx4 v[84:87], v[78:79], off offset:144
	v_lshl_add_u64 v[16:17], v[16:17], 0, s[96:97]
	s_mov_b32 s34, s45
	s_mov_b32 s35, 0
	v_lshl_add_u64 v[90:91], s[34:35], 1, v[40:41]
	global_load_dword v88, v[16:17], off
	global_load_dwordx4 v[92:95], v[90:91], off offset:128
	global_load_dwordx4 v[96:99], v[90:91], off offset:144
	v_lshl_add_u64 v[16:17], v[16:17], 0, s[96:97]
	s_mov_b64 s[34:35], 0xa00
	v_lshl_add_u64 v[102:103], s[34:35], 1, v[40:41]
	global_load_dword v100, v[16:17], off
	global_load_dwordx4 v[104:107], v[102:103], off offset:128
	global_load_dwordx4 v[108:111], v[102:103], off offset:144
	v_lshl_add_u64 v[16:17], v[16:17], 0, s[96:97]
	s_waitcnt vmcnt(11)
	v_add_f32_e32 v18, v18, v19
	s_waitcnt vmcnt(10)
	v_lshlrev_b32_e32 v28, 16, v20
	v_and_b32_e32 v29, 0xffff0000, v20
	v_lshlrev_b32_e32 v20, 16, v21
	v_and_b32_e32 v21, 0xffff0000, v21
	v_lshlrev_b32_e32 v30, 16, v22
	v_and_b32_e32 v31, 0xffff0000, v22
	v_lshlrev_b32_e32 v22, 16, v23
	v_and_b32_e32 v23, 0xffff0000, v23
	s_waitcnt vmcnt(9)
	v_lshlrev_b32_e32 v32, 16, v24
	v_and_b32_e32 v33, 0xffff0000, v24
	v_lshlrev_b32_e32 v24, 16, v25
	v_and_b32_e32 v25, 0xffff0000, v25
	v_lshlrev_b32_e32 v34, 16, v26
	v_and_b32_e32 v35, 0xffff0000, v26
	v_lshlrev_b32_e32 v26, 16, v27
	v_and_b32_e32 v27, 0xffff0000, v27
	v_pk_add_f32 v[14:15], v[14:15], v[28:29]
	v_pk_add_f32 v[12:13], v[12:13], v[20:21]
	v_pk_add_f32 v[10:11], v[10:11], v[30:31]
	v_pk_add_f32 v[6:7], v[6:7], v[22:23]
	v_pk_add_f32 v[8:9], v[8:9], v[32:33]
	v_pk_add_f32 v[4:5], v[4:5], v[24:25]
	v_pk_add_f32 v[2:3], v[2:3], v[34:35]
	v_pk_add_f32 v[0:1], v[0:1], v[26:27]
	s_waitcnt vmcnt(8)
	v_add_f32_e32 v18, v18, v76
	s_waitcnt vmcnt(7)
	v_lshlrev_b32_e32 v28, 16, v80
	v_and_b32_e32 v29, 0xffff0000, v80
	v_lshlrev_b32_e32 v80, 16, v81
	v_and_b32_e32 v81, 0xffff0000, v81
	v_lshlrev_b32_e32 v30, 16, v82
	v_and_b32_e32 v31, 0xffff0000, v82
	v_lshlrev_b32_e32 v82, 16, v83
	v_and_b32_e32 v83, 0xffff0000, v83
	s_waitcnt vmcnt(6)
	v_lshlrev_b32_e32 v32, 16, v84
	v_and_b32_e32 v33, 0xffff0000, v84
	v_lshlrev_b32_e32 v84, 16, v85
	v_and_b32_e32 v85, 0xffff0000, v85
	v_lshlrev_b32_e32 v34, 16, v86
	v_and_b32_e32 v35, 0xffff0000, v86
	v_lshlrev_b32_e32 v86, 16, v87
	v_and_b32_e32 v87, 0xffff0000, v87
	v_pk_add_f32 v[14:15], v[14:15], v[28:29]
	v_pk_add_f32 v[12:13], v[12:13], v[80:81]
	v_pk_add_f32 v[10:11], v[10:11], v[30:31]
	v_pk_add_f32 v[6:7], v[6:7], v[82:83]
	v_pk_add_f32 v[8:9], v[8:9], v[32:33]
	v_pk_add_f32 v[4:5], v[4:5], v[84:85]
	v_pk_add_f32 v[2:3], v[2:3], v[34:35]
	v_pk_add_f32 v[0:1], v[0:1], v[86:87]
	s_waitcnt vmcnt(5)
	v_add_f32_e32 v18, v18, v88
	s_waitcnt vmcnt(4)
	v_lshlrev_b32_e32 v28, 16, v92
	v_and_b32_e32 v29, 0xffff0000, v92
	v_lshlrev_b32_e32 v92, 16, v93
	v_and_b32_e32 v93, 0xffff0000, v93
	v_lshlrev_b32_e32 v30, 16, v94
	v_and_b32_e32 v31, 0xffff0000, v94
	v_lshlrev_b32_e32 v94, 16, v95
	v_and_b32_e32 v95, 0xffff0000, v95
	s_waitcnt vmcnt(3)
	v_lshlrev_b32_e32 v32, 16, v96
	v_and_b32_e32 v33, 0xffff0000, v96
	v_lshlrev_b32_e32 v96, 16, v97
	v_and_b32_e32 v97, 0xffff0000, v97
	v_lshlrev_b32_e32 v34, 16, v98
	v_and_b32_e32 v35, 0xffff0000, v98
	v_lshlrev_b32_e32 v98, 16, v99
	v_and_b32_e32 v99, 0xffff0000, v99
	v_pk_add_f32 v[14:15], v[14:15], v[28:29]
	v_pk_add_f32 v[12:13], v[12:13], v[92:93]
	v_pk_add_f32 v[10:11], v[10:11], v[30:31]
	v_pk_add_f32 v[6:7], v[6:7], v[94:95]
	v_pk_add_f32 v[8:9], v[8:9], v[32:33]
	v_pk_add_f32 v[4:5], v[4:5], v[96:97]
	v_pk_add_f32 v[2:3], v[2:3], v[34:35]
	v_pk_add_f32 v[0:1], v[0:1], v[98:99]
	s_waitcnt vmcnt(2)
	v_add_f32_e32 v18, v18, v100
	s_waitcnt vmcnt(1)
	v_lshlrev_b32_e32 v28, 16, v104
	v_and_b32_e32 v29, 0xffff0000, v104
	v_lshlrev_b32_e32 v104, 16, v105
	v_and_b32_e32 v105, 0xffff0000, v105
	v_lshlrev_b32_e32 v30, 16, v106
	v_and_b32_e32 v31, 0xffff0000, v106
	v_lshlrev_b32_e32 v106, 16, v107
	v_and_b32_e32 v107, 0xffff0000, v107
	s_waitcnt vmcnt(0)
	v_lshlrev_b32_e32 v32, 16, v108
	v_and_b32_e32 v33, 0xffff0000, v108
	v_lshlrev_b32_e32 v108, 16, v109
	v_and_b32_e32 v109, 0xffff0000, v109
	v_lshlrev_b32_e32 v34, 16, v110
	v_and_b32_e32 v35, 0xffff0000, v110
	v_lshlrev_b32_e32 v110, 16, v111
	v_and_b32_e32 v111, 0xffff0000, v111
	v_pk_add_f32 v[14:15], v[14:15], v[28:29]
	v_pk_add_f32 v[12:13], v[12:13], v[104:105]
	v_pk_add_f32 v[10:11], v[10:11], v[30:31]
	v_pk_add_f32 v[6:7], v[6:7], v[106:107]
	v_pk_add_f32 v[8:9], v[8:9], v[32:33]
	v_pk_add_f32 v[4:5], v[4:5], v[108:109]
	v_pk_add_f32 v[2:3], v[2:3], v[34:35]
	v_pk_add_f32 v[0:1], v[0:1], v[110:111]
	s_mov_b32 s6, 4
	s_branch .Lcmb1_done
.Lcmb1_one:
	s_waitcnt vmcnt(2)
	v_add_f32_e32 v18, v18, v19
	s_waitcnt vmcnt(1)
	v_lshlrev_b32_e32 v28, 16, v20
	v_and_b32_e32 v29, 0xffff0000, v20
	v_lshlrev_b32_e32 v20, 16, v21
	v_and_b32_e32 v21, 0xffff0000, v21
	v_lshlrev_b32_e32 v30, 16, v22
	v_and_b32_e32 v31, 0xffff0000, v22
	v_lshlrev_b32_e32 v22, 16, v23
	v_and_b32_e32 v23, 0xffff0000, v23
	s_waitcnt vmcnt(0)
	v_lshlrev_b32_e32 v32, 16, v24
	v_and_b32_e32 v33, 0xffff0000, v24
	v_lshlrev_b32_e32 v24, 16, v25
	v_and_b32_e32 v25, 0xffff0000, v25
	v_lshlrev_b32_e32 v34, 16, v26
	v_and_b32_e32 v35, 0xffff0000, v26
	v_lshlrev_b32_e32 v26, 16, v27
	v_and_b32_e32 v27, 0xffff0000, v27
	v_pk_add_f32 v[14:15], v[14:15], v[28:29]
	v_pk_add_f32 v[12:13], v[12:13], v[20:21]
	v_pk_add_f32 v[10:11], v[10:11], v[30:31]
	v_pk_add_f32 v[6:7], v[6:7], v[22:23]
	v_pk_add_f32 v[8:9], v[8:9], v[32:33]
	v_pk_add_f32 v[4:5], v[4:5], v[24:25]
	v_pk_add_f32 v[2:3], v[2:3], v[34:35]
	v_pk_add_f32 v[0:1], v[0:1], v[26:27]
	s_mov_b32 s6, 1

; DI void unpack8(u32x4 v, float* x) { x[0] = bflo(v.x); x[1] = bfhi(v.x); x[2] = bflo(v.y); x[3] = bfhi(v.y); x[4] = bflo(v.z); x[5] = bfhi(v.z); x[6] = bflo(v.w); x[7] = bfhi(v.w); }
; DI void combine_task(const Params& p, int layer, int tile) {
;     ...
;       for (int pi = 0; pi < nparts; ++pi) {
;         const int pcol = pi == 0 ? A_V : (pi == 1 ? A_Z : (pi == 2 ? B_V : D_X));
;         float a[16];
;         unpack8(*(const u32x4*)(row + pcol + col), a); unpack8(*(const u32x4*)(row + pcol + col + 8), a + 8);
; #pragma unroll
;         for (int e = 0; e < 16; ++e) o[e] += a[e];
;         l += lbuf[((size_t)pi * T_TOK + t) * 4 + h];
;       }
.LBB0_36:
.LBB0_37:
	s_mov_b64 s[34:35], 0x100
	v_lshl_add_u64 v[24:25], s[34:35], 1, v[40:41]
	global_load_dword v19, v[16:17], off
	global_load_dwordx4 v[20:23], v[24:25], off offset:256
	global_load_dwordx4 v[24:27], v[24:25], off offset:272
	v_lshl_add_u64 v[16:17], v[16:17], 0, s[96:97]
	s_and_b64 vcc, exec, s[0:1]
	s_cbranch_vccnz .Lcmb2_one
	s_mov_b64 s[34:35], 0x200
	v_lshl_add_u64 v[78:79], s[34:35], 1, v[40:41]
	global_load_dword v76, v[16:17], off
	global_load_dwordx4 v[80:83], v[78:79], off offset:256
	global_load_dwordx4 v[84:87], v[78:79], off offset:272
	v_lshl_add_u64 v[16:17], v[16:17], 0, s[96:97]
	s_mov_b32 s34, s45
	s_mov_b32 s35, 0
	v_lshl_add_u64 v[90:91], s[34:35], 1, v[40:41]
	global_load_dword v88, v[16:17], off
	global_load_dwordx4 v[92:95], v[90:91], off offset:256
	global_load_dwordx4 v[96:99], v[90:91], off offset:272
	v_lshl_add_u64 v[16:17], v[16:17], 0, s[96:97]
	s_mov_b64 s[34:35], 0xa00
	v_lshl_add_u64 v[102:103], s[34:35], 1, v[40:41]
	global_load_dword v100, v[16:17], off
	global_load_dwordx4 v[104:107], v[102:103], off offset:256
	global_load_dwordx4 v[108:111], v[102:103], off offset:272
	v_lshl_add_u64 v[16:17], v[16:17], 0, s[96:97]
	s_waitcnt vmcnt(11)
	v_add_f32_e32 v18, v18, v19
	s_waitcnt vmcnt(10)
	v_lshlrev_b32_e32 v28, 16, v20
	v_and_b32_e32 v29, 0xffff0000, v20
	v_lshlrev_b32_e32 v20, 16, v21
	v_and_b32_e32 v21, 0xffff0000, v21
	v_lshlrev_b32_e32 v30, 16, v22
	v_and_b32_e32 v31, 0xffff0000, v22
	v_lshlrev_b32_e32 v22, 16, v23
	v_and_b32_e32 v23, 0xffff0000, v23
	s_waitcnt vmcnt(9)
	v_lshlrev_b32_e32 v32, 16, v24
	v_and_b32_e32 v33, 0xffff0000, v24
	v_lshlrev_b32_e32 v24, 16, v25
	v_and_b32_e32 v25, 0xffff0000, v25
	v_lshlrev_b32_e32 v34, 16, v26
	v_and_b32_e32 v35, 0xffff0000, v26
	v_lshlrev_b32_e32 v26, 16, v27
	v_and_b32_e32 v27, 0xffff0000, v27
	v_pk_add_f32 v[14:15], v[14:15], v[28:29]
	v_pk_add_f32 v[12:13], v[12:13], v[20:21]
	v_pk_add_f32 v[10:11], v[10:11], v[30:31]
	v_pk_add_f32 v[6:7], v[6:7], v[22:23]
	v_pk_add_f32 v[8:9], v[8:9], v[32:33]
	v_pk_add_f32 v[4:5], v[4:5], v[24:25]
	v_pk_add_f32 v[2:3], v[2:3], v[34:35]
	v_pk_add_f32 v[0:1], v[0:1], v[26:27]
	s_waitcnt vmcnt(8)
	v_add_f32_e32 v18, v18, v76
	s_waitcnt vmcnt(7)
	v_lshlrev_b32_e32 v28, 16, v80
	v_and_b32_e32 v29, 0xffff0000, v80
	v_lshlrev_b32_e32 v80, 16, v81
	v_and_b32_e32 v81, 0xffff0000, v81
	v_lshlrev_b32_e32 v30, 16, v82
	v_and_b32_e32 v31, 0xffff0000, v82
	v_lshlrev_b32_e32 v82, 16, v83
	v_and_b32_e32 v83, 0xffff0000, v83
	s_waitcnt vmcnt(6)
	v_lshlrev_b32_e32 v32, 16, v84
	v_and_b32_e32 v33, 0xffff0000, v84
	v_lshlrev_b32_e32 v84, 16, v85
	v_and_b32_e32 v85, 0xffff0000, v85
	v_lshlrev_b32_e32 v34, 16, v86
	v_and_b32_e32 v35, 0xffff0000, v86
	v_lshlrev_b32_e32 v86, 16, v87
	v_and_b32_e32 v87, 0xffff0000, v87
	v_pk_add_f32 v[14:15], v[14:15], v[28:29]
	v_pk_add_f32 v[12:13], v[12:13], v[80:81]
	v_pk_add_f32 v[10:11], v[10:11], v[30:31]
	v_pk_add_f32 v[6:7], v[6:7], v[82:83]
	v_pk_add_f32 v[8:9], v[8:9], v[32:33]
	v_pk_add_f32 v[4:5], v[4:5], v[84:85]
	v_pk_add_f32 v[2:3], v[2:3], v[34:35]
	v_pk_add_f32 v[0:1], v[0:1], v[86:87]
	s_waitcnt vmcnt(5)
	v_add_f32_e32 v18, v18, v88
	s_waitcnt vmcnt(4)
	v_lshlrev_b32_e32 v28, 16, v92
	v_and_b32_e32 v29, 0xffff0000, v92
	v_lshlrev_b32_e32 v92, 16, v93
	v_and_b32_e32 v93, 0xffff0000, v93
	v_lshlrev_b32_e32 v30, 16, v94
	v_and_b32_e32 v31, 0xffff0000, v94
	v_lshlrev_b32_e32 v94, 16, v95
	v_and_b32_e32 v95, 0xffff0000, v95
	s_waitcnt vmcnt(3)
	v_lshlrev_b32_e32 v32, 16, v96
	v_and_b32_e32 v33, 0xffff0000, v96
	v_lshlrev_b32_e32 v96, 16, v97
	v_and_b32_e32 v97, 0xffff0000, v97
	v_lshlrev_b32_e32 v34, 16, v98
	v_and_b32_e32 v35, 0xffff0000, v98
	v_lshlrev_b32_e32 v98, 16, v99
	v_and_b32_e32 v99, 0xffff0000, v99
	v_pk_add_f32 v[14:15], v[14:15], v[28:29]
	v_pk_add_f32 v[12:13], v[12:13], v[92:93]
	v_pk_add_f32 v[10:11], v[10:11], v[30:31]
	v_pk_add_f32 v[6:7], v[6:7], v[94:95]
	v_pk_add_f32 v[8:9], v[8:9], v[32:33]
	v_pk_add_f32 v[4:5], v[4:5], v[96:97]
	v_pk_add_f32 v[2:3], v[2:3], v[34:35]
	v_pk_add_f32 v[0:1], v[0:1], v[98:99]
	s_waitcnt vmcnt(2)
	v_add_f32_e32 v18, v18, v100
	s_waitcnt vmcnt(1)
	v_lshlrev_b32_e32 v28, 16, v104
	v_and_b32_e32 v29, 0xffff0000, v104
	v_lshlrev_b32_e32 v104, 16, v105
	v_and_b32_e32 v105, 0xffff0000, v105
	v_lshlrev_b32_e32 v30, 16, v106
	v_and_b32_e32 v31, 0xffff0000, v106
	v_lshlrev_b32_e32 v106, 16, v107
	v_and_b32_e32 v107, 0xffff0000, v107
	s_waitcnt vmcnt(0)
	v_lshlrev_b32_e32 v32, 16, v108
	v_and_b32_e32 v33, 0xffff0000, v108
	v_lshlrev_b32_e32 v108, 16, v109
	v_and_b32_e32 v109, 0xffff0000, v109
	v_lshlrev_b32_e32 v34, 16, v110
	v_and_b32_e32 v35, 0xffff0000, v110
	v_lshlrev_b32_e32 v110, 16, v111
	v_and_b32_e32 v111, 0xffff0000, v111
	v_pk_add_f32 v[14:15], v[14:15], v[28:29]
	v_pk_add_f32 v[12:13], v[12:13], v[104:105]
	v_pk_add_f32 v[10:11], v[10:11], v[30:31]
	v_pk_add_f32 v[6:7], v[6:7], v[106:107]
	v_pk_add_f32 v[8:9], v[8:9], v[32:33]
	v_pk_add_f32 v[4:5], v[4:5], v[108:109]
	v_pk_add_f32 v[2:3], v[2:3], v[34:35]
	v_pk_add_f32 v[0:1], v[0:1], v[110:111]
	s_mov_b32 s6, 4
	s_branch .Lcmb2_done

; DI void unpack8(u32x4 v, float* x) { x[0] = bflo(v.x); x[1] = bfhi(v.x); x[2] = bflo(v.y); x[3] = bfhi(v.y); x[4] = bflo(v.z); x[5] = bfhi(v.z); x[6] = bflo(v.w); x[7] = bfhi(v.w); }
; DI void combine_task(const Params& p, int layer, int tile) {
;     ...
;       for (int pi = 0; pi < nparts; ++pi) {
;         const int pcol = pi == 0 ? A_V : (pi == 1 ? A_Z : (pi == 2 ? B_V : D_X));
;         float a[16];
;         unpack8(*(const u32x4*)(row + pcol + col), a); unpack8(*(const u32x4*)(row + pcol + col + 8), a + 8);
; #pragma unroll
;         for (int e = 0; e < 16; ++e) o[e] += a[e];
;         l += lbuf[((size_t)pi * T_TOK + t) * 4 + h];
;       }
.LBB0_43:
.LBB0_44:
	s_mov_b64 s[34:35], 0x100
	v_lshl_add_u64 v[2:3], s[34:35], 1, v[40:41]
	global_load_dword v8, v[0:1], off
	global_load_dwordx4 v[24:27], v[2:3], off offset:384
	global_load_dwordx4 v[28:31], v[2:3], off offset:400
	v_lshl_add_u64 v[0:1], v[0:1], 0, s[96:97]
	s_and_b64 vcc, exec, s[0:1]
	s_cbranch_vccnz .Lcmb3_one
	s_mov_b64 s[34:35], 0x200
	v_lshl_add_u64 v[78:79], s[34:35], 1, v[40:41]
	global_load_dword v76, v[0:1], off
	global_load_dwordx4 v[80:83], v[78:79], off offset:384
	global_load_dwordx4 v[84:87], v[78:79], off offset:400
	v_lshl_add_u64 v[0:1], v[0:1], 0, s[96:97]
	s_mov_b32 s34, s45
	s_mov_b32 s35, 0
	v_lshl_add_u64 v[90:91], s[34:35], 1, v[40:41]
	global_load_dword v88, v[0:1], off
	global_load_dwordx4 v[92:95], v[90:91], off offset:384
	global_load_dwordx4 v[96:99], v[90:91], off offset:400
	v_lshl_add_u64 v[0:1], v[0:1], 0, s[96:97]
	s_mov_b64 s[34:35], 0xa00
	v_lshl_add_u64 v[102:103], s[34:35], 1, v[40:41]
	global_load_dword v100, v[0:1], off
	global_load_dwordx4 v[104:107], v[102:103], off offset:384
	global_load_dwordx4 v[108:111], v[102:103], off offset:400
	v_lshl_add_u64 v[0:1], v[0:1], 0, s[96:97]
	s_waitcnt vmcnt(11)
	v_add_f32_e32 v12, v12, v8
	s_waitcnt vmcnt(10)
	v_lshlrev_b32_e32 v2, 16, v24
	v_and_b32_e32 v3, 0xffff0000, v24
	v_lshlrev_b32_e32 v8, 16, v25
	v_and_b32_e32 v9, 0xffff0000, v25
	v_lshlrev_b32_e32 v24, 16, v26
	v_and_b32_e32 v25, 0xffff0000, v26
	v_lshlrev_b32_e32 v26, 16, v27
	v_and_b32_e32 v27, 0xffff0000, v27
	s_waitcnt vmcnt(9)
	v_lshlrev_b32_e32 v32, 16, v28
	v_and_b32_e32 v33, 0xffff0000, v28
	v_lshlrev_b32_e32 v28, 16, v29
	v_and_b32_e32 v29, 0xffff0000, v29
	v_lshlrev_b32_e32 v34, 16, v30
	v_and_b32_e32 v35, 0xffff0000, v30
	v_lshlrev_b32_e32 v30, 16, v31
	v_and_b32_e32 v31, 0xffff0000, v31
	v_pk_add_f32 v[10:11], v[10:11], v[2:3]
	v_pk_add_f32 v[14:15], v[14:15], v[8:9]
	v_pk_add_f32 v[18:19], v[18:19], v[24:25]
	v_pk_add_f32 v[22:23], v[22:23], v[26:27]
	v_pk_add_f32 v[20:21], v[20:21], v[32:33]
	v_pk_add_f32 v[16:17], v[16:17], v[28:29]
	v_pk_add_f32 v[6:7], v[6:7], v[34:35]
	v_pk_add_f32 v[4:5], v[4:5], v[30:31]
	s_waitcnt vmcnt(8)
	v_add_f32_e32 v12, v12, v76
	s_waitcnt vmcnt(7)
	v_lshlrev_b32_e32 v2, 16, v80
	v_and_b32_e32 v3, 0xffff0000, v80
	v_lshlrev_b32_e32 v8, 16, v81
	v_and_b32_e32 v9, 0xffff0000, v81
	v_lshlrev_b32_e32 v80, 16, v82
	v_and_b32_e32 v81, 0xffff0000, v82
	v_lshlrev_b32_e32 v82, 16, v83
	v_and_b32_e32 v83, 0xffff0000, v83
	s_waitcnt vmcnt(6)
	v_lshlrev_b32_e32 v32, 16, v84
	v_and_b32_e32 v33, 0xffff0000, v84
	v_lshlrev_b32_e32 v84, 16, v85
	v_and_b32_e32 v85, 0xffff0000, v85
	v_lshlrev_b32_e32 v34, 16, v86
	v_and_b32_e32 v35, 0xffff0000, v86
	v_lshlrev_b32_e32 v86, 16, v87
	v_and_b32_e32 v87, 0xffff0000, v87
	v_pk_add_f32 v[10:11], v[10:11], v[2:3]
	v_pk_add_f32 v[14:15], v[14:15], v[8:9]
	v_pk_add_f32 v[18:19], v[18:19], v[80:81]
	v_pk_add_f32 v[22:23], v[22:23], v[82:83]
	v_pk_add_f32 v[20:21], v[20:21], v[32:33]
	v_pk_add_f32 v[16:17], v[16:17], v[84:85]
	v_pk_add_f32 v[6:7], v[6:7], v[34:35]
	v_pk_add_f32 v[4:5], v[4:5], v[86:87]
	s_waitcnt vmcnt(5)
	v_add_f32_e32 v12, v12, v88
	s_waitcnt vmcnt(4)
	v_lshlrev_b32_e32 v2, 16, v92
	v_and_b32_e32 v3, 0xffff0000, v92
	v_lshlrev_b32_e32 v8, 16, v93
	v_and_b32_e32 v9, 0xffff0000, v93
	v_lshlrev_b32_e32 v92, 16, v94
	v_and_b32_e32 v93, 0xffff0000, v94
	v_lshlrev_b32_e32 v94, 16, v95
	v_and_b32_e32 v95, 0xffff0000, v95
	s_waitcnt vmcnt(3)
	v_lshlrev_b32_e32 v32, 16, v96
	v_and_b32_e32 v33, 0xffff0000, v96
	v_lshlrev_b32_e32 v96, 16, v97
	v_and_b32_e32 v97, 0xffff0000, v97
	v_lshlrev_b32_e32 v34, 16, v98
	v_and_b32_e32 v35, 0xffff0000, v98
	v_lshlrev_b32_e32 v98, 16, v99
	v_and_b32_e32 v99, 0xffff0000, v99
	v_pk_add_f32 v[10:11], v[10:11], v[2:3]
	v_pk_add_f32 v[14:15], v[14:15], v[8:9]
	v_pk_add_f32 v[18:19], v[18:19], v[92:93]
	v_pk_add_f32 v[22:23], v[22:23], v[94:95]
	v_pk_add_f32 v[20:21], v[20:21], v[32:33]
	v_pk_add_f32 v[16:17], v[16:17], v[96:97]
	v_pk_add_f32 v[6:7], v[6:7], v[34:35]
	v_pk_add_f32 v[4:5], v[4:5], v[98:99]
	s_waitcnt vmcnt(2)
	v_add_f32_e32 v12, v12, v100
	s_waitcnt vmcnt(1)
	v_lshlrev_b32_e32 v2, 16, v104
	v_and_b32_e32 v3, 0xffff0000, v104
	v_lshlrev_b32_e32 v8, 16, v105
	v_and_b32_e32 v9, 0xffff0000, v105
	v_lshlrev_b32_e32 v104, 16, v106
	v_and_b32_e32 v105, 0xffff0000, v106
	v_lshlrev_b32_e32 v106, 16, v107
	v_and_b32_e32 v107, 0xffff0000, v107
	s_waitcnt vmcnt(0)
	v_lshlrev_b32_e32 v32, 16, v108
	v_and_b32_e32 v33, 0xffff0000, v108
	v_lshlrev_b32_e32 v108, 16, v109
	v_and_b32_e32 v109, 0xffff0000, v109
	v_lshlrev_b32_e32 v34, 16, v110
	v_and_b32_e32 v35, 0xffff0000, v110
	v_lshlrev_b32_e32 v110, 16, v111
	v_and_b32_e32 v111, 0xffff0000, v111
	v_pk_add_f32 v[10:11], v[10:11], v[2:3]
	v_pk_add_f32 v[14:15], v[14:15], v[8:9]
	v_pk_add_f32 v[18:19], v[18:19], v[104:105]
	v_pk_add_f32 v[22:23], v[22:23], v[106:107]
	v_pk_add_f32 v[20:21], v[20:21], v[32:33]
	v_pk_add_f32 v[16:17], v[16:17], v[108:109]
	v_pk_add_f32 v[6:7], v[6:7], v[34:35]
	v_pk_add_f32 v[4:5], v[4:5], v[110:111]
	s_mov_b32 s6, 4
	s_branch .Lcmb3_done
.Lcmb3_one:
	s_waitcnt vmcnt(2)
	v_add_f32_e32 v12, v12, v8
	s_waitcnt vmcnt(1)
	v_lshlrev_b32_e32 v2, 16, v24
	v_and_b32_e32 v3, 0xffff0000, v24
	v_lshlrev_b32_e32 v8, 16, v25
	v_and_b32_e32 v9, 0xffff0000, v25
	v_lshlrev_b32_e32 v24, 16, v26
	v_and_b32_e32 v25, 0xffff0000, v26
	v_lshlrev_b32_e32 v26, 16, v27
	v_and_b32_e32 v27, 0xffff0000, v27
	s_waitcnt vmcnt(0)
	v_lshlrev_b32_e32 v32, 16, v28
	v_and_b32_e32 v33, 0xffff0000, v28
	v_lshlrev_b32_e32 v28, 16, v29
	v_and_b32_e32 v29, 0xffff0000, v29
	v_lshlrev_b32_e32 v34, 16, v30
	v_and_b32_e32 v35, 0xffff0000, v30
	v_lshlrev_b32_e32 v30, 16, v31
	v_and_b32_e32 v31, 0xffff0000, v31
	v_pk_add_f32 v[10:11], v[10:11], v[2:3]
	v_pk_add_f32 v[14:15], v[14:15], v[8:9]
	v_pk_add_f32 v[18:19], v[18:19], v[24:25]
	v_pk_add_f32 v[22:23], v[22:23], v[26:27]
	v_pk_add_f32 v[20:21], v[20:21], v[32:33]
	v_pk_add_f32 v[16:17], v[16:17], v[28:29]
	v_pk_add_f32 v[6:7], v[6:7], v[34:35]
	v_pk_add_f32 v[4:5], v[4:5], v[30:31]
	s_mov_b32 s6, 1
